# MLP2 epilogue: per-row sum-of-squares lane reduction with v_permlane16/32_swap instead of ds_bpermute (8 sites)
# baseline (speedup 1.0000x reference)
; DEVI void phase_resid_gemm(const Params& p, const bfu* A, int lda, int nkt, const bfu* wT, int ldb, const float* resid32,
;                            float* ssq_out, float* out32, char* lds) {
;     ...
;       if (!out32) {
;         ss += __shfl_xor(ss, 16);
;         ss += __shfl_xor(ss, 32);
;         if (fq == 0) part[(wm * 128 + mi * 16 + fr) * 4 + wn] = ss;
;       }
.LBB0_55:
	v_mov_b32_e32 v110, v0
	s_nop 1
	v_permlane16_swap_b32_e32 v0, v110
	v_add_f32_e32 v0, v0, v110
	v_mov_b32_e32 v110, v0
	s_nop 1
	v_permlane32_swap_b32_e32 v0, v110
	s_and_saveexec_b64 s[36:37], s[38:39]
	s_cbranch_execz .LBB0_57
	s_waitcnt lgkmcnt(0)
	v_add_f32_e32 v0, v0, v110
	v_add_u32_e32 v110, v183, v184
	ds_write_b32 v110, v0

; DEVI void phase_resid_gemm(const Params& p, const bfu* A, int lda, int nkt, const bfu* wT, int ldb, const float* resid32,
;                            float* ssq_out, float* out32, char* lds) {
;     ...
;       if (!out32) {
;         ss += __shfl_xor(ss, 16);
;         ss += __shfl_xor(ss, 32);
;         if (fq == 0) part[(wm * 128 + mi * 16 + fr) * 4 + wn] = ss;
;       }
.LBB0_75:
	v_mov_b32_e32 v94, v0
	s_nop 1
	v_permlane16_swap_b32_e32 v0, v94
	v_add_f32_e32 v0, v0, v94
	v_mov_b32_e32 v94, v0
	s_nop 1
	v_permlane32_swap_b32_e32 v0, v94
	s_and_saveexec_b64 s[36:37], s[38:39]
	s_cbranch_execz .LBB0_77
	s_waitcnt lgkmcnt(0)
	v_add_f32_e32 v0, v0, v94
	v_add_u32_e32 v94, v183, v184
	ds_write_b32 v94, v0 offset:256

; DEVI void phase_resid_gemm(const Params& p, const bfu* A, int lda, int nkt, const bfu* wT, int ldb, const float* resid32,
;                            float* ssq_out, float* out32, char* lds) {
;     ...
;       if (!out32) {
;         ss += __shfl_xor(ss, 16);
;         ss += __shfl_xor(ss, 32);
;         if (fq == 0) part[(wm * 128 + mi * 16 + fr) * 4 + wn] = ss;
;       }
.LBB0_95:
	v_mov_b32_e32 v78, v0
	s_nop 1
	v_permlane16_swap_b32_e32 v0, v78
	v_add_f32_e32 v0, v0, v78
	v_mov_b32_e32 v78, v0
	s_nop 1
	v_permlane32_swap_b32_e32 v0, v78
	s_and_saveexec_b64 s[36:37], s[38:39]
	s_cbranch_execz .LBB0_97
	s_waitcnt lgkmcnt(0)
	v_add_f32_e32 v0, v0, v78
	v_add_u32_e32 v78, v183, v184
	ds_write_b32 v78, v0 offset:512

; DEVI void phase_resid_gemm(const Params& p, const bfu* A, int lda, int nkt, const bfu* wT, int ldb, const float* resid32,
;                            float* ssq_out, float* out32, char* lds) {
;     ...
;       if (!out32) {
;         ss += __shfl_xor(ss, 16);
;         ss += __shfl_xor(ss, 32);
;         if (fq == 0) part[(wm * 128 + mi * 16 + fr) * 4 + wn] = ss;
;       }
.LBB0_115:
	v_mov_b32_e32 v62, v0
	s_nop 1
	v_permlane16_swap_b32_e32 v0, v62
	v_add_f32_e32 v0, v0, v62
	v_mov_b32_e32 v62, v0
	s_nop 1
	v_permlane32_swap_b32_e32 v0, v62
	s_and_saveexec_b64 s[36:37], s[38:39]
	s_cbranch_execz .LBB0_117
	s_waitcnt lgkmcnt(0)
	v_add_f32_e32 v0, v0, v62
	v_add_u32_e32 v62, v183, v184
	ds_write_b32 v62, v0 offset:768

; DEVI void phase_resid_gemm(const Params& p, const bfu* A, int lda, int nkt, const bfu* wT, int ldb, const float* resid32,
;                            float* ssq_out, float* out32, char* lds) {
;     ...
;       if (!out32) {
;         ss += __shfl_xor(ss, 16);
;         ss += __shfl_xor(ss, 32);
;         if (fq == 0) part[(wm * 128 + mi * 16 + fr) * 4 + wn] = ss;
;       }
.LBB0_135:
	v_mov_b32_e32 v46, v0
	s_nop 1
	v_permlane16_swap_b32_e32 v0, v46
	v_add_f32_e32 v0, v0, v46
	v_mov_b32_e32 v46, v0
	s_nop 1
	v_permlane32_swap_b32_e32 v0, v46
	s_and_saveexec_b64 s[36:37], s[38:39]
	s_cbranch_execz .LBB0_137
	s_waitcnt lgkmcnt(0)
	v_add_f32_e32 v0, v0, v46
	v_add_u32_e32 v46, v183, v184
	ds_write_b32 v46, v0 offset:1024

; DEVI void phase_resid_gemm(const Params& p, const bfu* A, int lda, int nkt, const bfu* wT, int ldb, const float* resid32,
;                            float* ssq_out, float* out32, char* lds) {
;     ...
;       if (!out32) {
;         ss += __shfl_xor(ss, 16);
;         ss += __shfl_xor(ss, 32);
;         if (fq == 0) part[(wm * 128 + mi * 16 + fr) * 4 + wn] = ss;
;       }
.LBB0_155:
	v_mov_b32_e32 v30, v0
	s_nop 1
	v_permlane16_swap_b32_e32 v0, v30
	v_add_f32_e32 v0, v0, v30
	v_mov_b32_e32 v30, v0
	s_nop 1
	v_permlane32_swap_b32_e32 v0, v30
	s_and_saveexec_b64 s[36:37], s[38:39]
	s_cbranch_execz .LBB0_157
	s_waitcnt lgkmcnt(0)
	v_add_f32_e32 v0, v0, v30
	v_add_u32_e32 v30, v183, v184
	ds_write_b32 v30, v0 offset:1280

; DEVI void phase_resid_gemm(const Params& p, const bfu* A, int lda, int nkt, const bfu* wT, int ldb, const float* resid32,
;                            float* ssq_out, float* out32, char* lds) {
;     ...
;       if (!out32) {
;         ss += __shfl_xor(ss, 16);
;         ss += __shfl_xor(ss, 32);
;         if (fq == 0) part[(wm * 128 + mi * 16 + fr) * 4 + wn] = ss;
;       }
.LBB0_175:
	v_mov_b32_e32 v18, v0
	s_nop 1
	v_permlane16_swap_b32_e32 v0, v18
	v_add_f32_e32 v0, v0, v18
	v_mov_b32_e32 v18, v0
	s_nop 1
	v_permlane32_swap_b32_e32 v0, v18
	s_and_saveexec_b64 s[36:37], s[38:39]
	s_cbranch_execz .LBB0_177
	s_waitcnt lgkmcnt(0)
	v_add_f32_e32 v0, v0, v18
	v_add_u32_e32 v18, v183, v184
	ds_write_b32 v18, v0 offset:1536

; DEVI void phase_resid_gemm(const Params& p, const bfu* A, int lda, int nkt, const bfu* wT, int ldb, const float* resid32,
;                            float* ssq_out, float* out32, char* lds) {
;     ...
;       if (!out32) {
;         ss += __shfl_xor(ss, 16);
;         ss += __shfl_xor(ss, 32);
;         if (fq == 0) part[(wm * 128 + mi * 16 + fr) * 4 + wn] = ss;
;       }
.LBB0_195:
	v_mov_b32_e32 v2, v0
	s_nop 1
	v_permlane16_swap_b32_e32 v0, v2
	v_add_f32_e32 v0, v0, v2
	v_mov_b32_e32 v2, v0
	s_nop 1
	v_permlane32_swap_b32_e32 v0, v2
	s_and_saveexec_b64 s[36:37], s[38:39]
	s_cbranch_execz .LBB0_197
	s_waitcnt lgkmcnt(0)
	v_add_f32_e32 v0, v0, v2
	v_add_u32_e32 v2, v183, v184
	ds_write_b32 v2, v0 offset:1792
